# spin loops without s_sleep back-off (31 sites) on top of K-loop barrier-path trims
# speedup vs baseline: 1.0001x; 1.0001x over previous
; __global__ void __launch_bounds__(NWAVES * 64, 2) fwd_kernel(Args args) {
;     ...
;     if (hi > NPHASE) cg::this_grid().sync();
.LBB0_12:
	global_load_dword v2, v0, s[4:5] offset:32 sc1
	s_waitcnt vmcnt(0)
	v_and_b32_e32 v2, 0xffff0000, v2
	v_cmp_ne_u32_e32 vcc, v2, v1
	s_or_b64 s[6:7], vcc, s[6:7]
	s_andn2_b64 exec, exec, s[6:7]
	s_cbranch_execnz .LBB0_12

; __device__ __forceinline__ unsigned xb_ld(unsigned* p) { return __hip_atomic_load(p, __ATOMIC_RELAXED, __HIP_MEMORY_SCOPE_AGENT); }
; __device__ __forceinline__ void grid_barrier(unsigned* barw, int k, volatile LAS unsigned* st) {
;     ...
;             for (;;) { unsigned sum = 0u, cnt = 0u, mine = 0u;
; #pragma unroll
;                 for (unsigned j = 0; j < 16; ++j) { const unsigned c = xb_ld(barw + 64 * j); sum += c; cnt += (c > 0u) ? 1u : 0u; mine = (j == x) ? c : mine; }
;                 if (sum == G) { nloc = mine; nx = cnt; break; }
;                 __builtin_amdgcn_s_sleep(1); }
.LBB0_120:
	s_andn2_b64 vcc, exec, s[36:37]
	s_cbranch_vccz .LBB0_123

; __device__ __forceinline__ unsigned xb_ld(unsigned* p) { return __hip_atomic_load(p, __ATOMIC_RELAXED, __HIP_MEMORY_SCOPE_AGENT); }
; __device__ __forceinline__ void grid_barrier(unsigned* barw, int k, volatile LAS unsigned* st) {
;     ...
;             else while (xb_ld(sb + 2112) == 0u) __builtin_amdgcn_s_sleep(1);
.LBB0_129:
	global_load_dword v1, v0, s[2:3] sc1
	s_waitcnt vmcnt(0)
	v_cmp_eq_u32_e32 vcc, 0, v1
	s_cbranch_vccnz .LBB0_129

; __device__ __forceinline__ unsigned xb_ld(unsigned* p) { return __hip_atomic_load(p, __ATOMIC_RELAXED, __HIP_MEMORY_SCOPE_AGENT); }
; __device__ __forceinline__ void grid_barrier(unsigned* barw, int k, volatile LAS unsigned* st) {
;     ...
;             while (xb_ld(sb + 1024 + 64 * x) == 0u) __builtin_amdgcn_s_sleep(1);
.LBB0_136:
	global_load_dword v1, v0, s[0:1] sc1
	s_waitcnt vmcnt(0)
	v_cmp_eq_u32_e32 vcc, 0, v1
	s_cbranch_vccnz .LBB0_136

; __device__ __forceinline__ unsigned xb_ld(unsigned* p) { return __hip_atomic_load(p, __ATOMIC_RELAXED, __HIP_MEMORY_SCOPE_AGENT); }
; __device__ __forceinline__ void grid_barrier(unsigned* barw, int k, volatile LAS unsigned* st) {
;     ...
;             while (xb_ld(sb + 1024 + 64 * x) == 0u) __builtin_amdgcn_s_sleep(1);
.Lgb4_spin:
	global_load_dword v2, v0, s[4:5] sc1
	s_waitcnt vmcnt(0)
	v_readfirstlane_b32 s7, v2
	s_cmp_ge_u32 s7, s6
	s_cbranch_scc1 .Lgb4_acq
	s_branch .Lgb4_spin

; #define LAS __attribute__((address_space(3)))
; #define SEAM(k) do { if (IN(k) && IN((k) + 1)) { grid_barrier(barw, (k), bst); } } while (0)
; __global__ void __launch_bounds__(NWAVES * 64, 2) fwd_kernel(Args args) {
;     ...
;         if (G >= 256 && blockIdx.x >= 128) {
;             const int wave = threadIdx.x >> 6, lane = threadIdx.x & 63;
;             LAS float* scr = (LAS float*)(lds + wave * 8704);
;             const int gw = ((int)blockIdx.x - 128) * NWAVES + wave, NGW = (G - 128) * NWAVES;
;             constexpr int I_O = 16 * 32, I_1 = 16 * 128, I_2 = 64 * 32;
;             for (int it = gw; it < I_O + I_1 + I_2; it += NGW) {
;                 int r = it;
;                 if (r < I_O) { transpose_item<0>(args.in[12], 1024, 1024, (bf16_t*)(ws + WS_WOUT), args.in[11], scr, r, 32, lane); continue; } r -= I_O;
;                 if (r < I_1) { transpose_item<0>(args.in[14], 1024, 4096, (bf16_t*)(ws + WS_WFF1), args.in[13], scr, r, 128, lane); continue; } r -= I_1;
;                 transpose_item<0>(args.in[15], 4096, 1024, (bf16_t*)(ws + WS_WFF2), nullptr, scr, r, 32, lane);
;             }
;         } else {
;             pg8::CmpOrder So{G >= 256 ? 128 : G, (int)blockIdx.x};
;             EpiPart E{(float*)(ws + WS_PART)};
;             pg8::gemm_phase<EpiPart, pg8::CmpOrder, false, true>(lds, g, So, E);
;         }
;     }
;     SEAM(2);
.Lgb2_pf:
	global_load_dword v2, v0, s[4:5] sc1
	s_waitcnt vmcnt(0)
	v_readfirstlane_b32 s7, v2
	s_cmp_ge_u32 s7, 128
	s_cbranch_scc1 .Lgb2_pfok
	s_branch .Lgb2_pf

; template <class Epi, class Sched, bool ALIGN_EPI = false, bool SP2 = false>
; __device__ __forceinline__ void gemm_phase(PG8_LAS unsigned char* lds, const Gemm g, const Sched& S, const Epi& E) {
;     ...
;             if (last && has_next) S.a_ready(nxt);
.Lx_poll:
	v_mov_b32_e32 v250, 0
	global_load_dword v250, v250, s[100:101] sc1
	s_waitcnt vmcnt(0)
	v_readfirstlane_b32 s99, v250
	s_cmp_ge_u32 s99, s88
	s_cbranch_scc1 .Lx_set
	s_branch .Lx_poll

; template <class Epi, class Sched, bool ALIGN_EPI = false, bool SP2 = false>
; __device__ __forceinline__ void gemm_phase(PG8_LAS unsigned char* lds, const Gemm g, const Sched& S, const Epi& E) {
;     ...
;             if (last && has_next) S.a_ready(nxt);
.Lh_poll:
	v_mov_b32_e32 v128, 0
	global_load_dword v128, v128, s[100:101] sc1
	s_waitcnt vmcnt(0)
	v_readfirstlane_b32 s99, v128
	s_cmp_ge_u32 s99, s88
	s_cbranch_scc1 .Lh_set
	s_branch .Lh_poll

; __device__ __forceinline__ unsigned xb_ld(unsigned* p) { return __hip_atomic_load(p, __ATOMIC_RELAXED, __HIP_MEMORY_SCOPE_AGENT); }
; __device__ __forceinline__ void grid_barrier(unsigned* barw, int k, volatile LAS unsigned* st) {
;     ...
;             for (;;) { unsigned sum = 0u, cnt = 0u, mine = 0u;
; #pragma unroll
;                 for (unsigned j = 0; j < 16; ++j) { const unsigned c = xb_ld(barw + 64 * j); sum += c; cnt += (c > 0u) ? 1u : 0u; mine = (j == x) ? c : mine; }
;                 if (sum == G) { nloc = mine; nx = cnt; break; }
;                 __builtin_amdgcn_s_sleep(1); }
.LBB0_1018:
	s_andn2_b64 vcc, exec, s[34:35]
	s_cbranch_vccz .LBB0_1021
